# v10 + cache-K conversion (prologue_b kc_item) de-serialised: 8 row loads in flight with counted waits instead of 4 load-wait-store round trips
# speedup vs baseline: 1.0062x; 1.0062x over previous
; DI void kc_item(const float* src, int past, int nh, int band, int krows, bf16_t* KF, int item, int lane) {
;     const int nrb = past / 32, h = item % nh, rb = (item / nh) % nrb, b = item / (nh * nrb), r = lane & 31, hh = lane >> 5;
;     const float* sp = src + (((size_t)b * past + rb * 32 + r) * nh + h) * 64 + 8 * hh;
;     bf16_t* d = KF + (((size_t)h * (krows >> 5) + ((SEQ + b * band) >> 5) + rb) * 4 * 64 + lane) * 8;
; #pragma unroll
;     for (int ds = 0; ds < 4; ++ds) { const f32x4 v0 = *(const f32x4*)(sp + 16 * ds), v1 = *(const f32x4*)(sp + 16 * ds + 4);
;         u32x4 o; o.x = pk2(v0[0], v0[1]); o.y = pk2(v0[2], v0[3]); o.z = pk2(v1[0], v1[1]); o.w = pk2(v1[2], v1[3]);
;         *(u32x4*)(d + ds * 512) = o; }
; }
; DI void prologue_b(KArgs ap, int gw, int NGW, int lane) {
;     ...
;     for (int it = gw; it < NSTREAM * 16 * 8; it += NGW) kc_item(cak, 512, 8, 576, KA_ROWS, (bf16_t*)(ws + WS_KA), it, lane);
.LBB0_537:
	s_ashr_i32 s11, s10, 31
	s_lshr_b32 s18, s11, 29
	s_lshr_b32 s11, s11, 25
	s_add_i32 s18, s10, s18
	s_add_i32 s11, s10, s11
	s_ashr_i32 s26, s18, 3
	s_and_b32 s19, s18, -8
	s_ashr_i32 s18, s11, 7
	s_lshr_b32 s11, s26, 28
	s_add_i32 s11, s26, s11
	s_and_b32 s11, s11, -16
	s_sub_i32 s20, s10, s19
	s_ashr_i32 s19, s18, 31
	s_sub_i32 s11, s26, s11
	s_ashr_i32 s21, s20, 31
	s_lshl_b64 s[22:23], s[18:19], 20
	s_lshl_b32 s19, s11, 5
	s_lshl_b64 s[24:25], s[20:21], 8
	s_ashr_i32 s21, s19, 31
	v_or_b32_e32 v6, s19, v0
	v_mov_b32_e32 v7, s21
	v_lshlrev_b64 v[6:7], 11, v[6:7]
	v_lshl_add_u64 v[6:7], v[2:3], 0, v[6:7]
	v_lshl_add_u64 v[6:7], v[6:7], 0, s[22:23]
	v_lshl_add_u64 v[14:15], v[6:7], 0, s[24:25]
	global_load_dwordx4 v[6:9], v[14:15], off
	global_load_dwordx4 v[10:13], v[14:15], off offset:16
	global_load_dwordx4 v[44:47], v[14:15], off offset:64
	global_load_dwordx4 v[48:51], v[14:15], off offset:80
	global_load_dwordx4 v[52:55], v[14:15], off offset:128
	global_load_dwordx4 v[56:59], v[14:15], off offset:144
	global_load_dwordx4 v[60:63], v[14:15], off offset:192
	global_load_dwordx4 v[64:67], v[14:15], off offset:208
	s_mulk_i32 s18, 0x240
	s_addk_i32 s18, 0x4000
	s_ashr_i32 s18, s18, 5
	s_mul_hi_i32 s19, s20, 0x440
	s_mulk_i32 s20, 0x440
	s_ashr_i32 s21, s18, 31
	s_ashr_i32 s22, s11, 31
	s_add_u32 s11, s20, s11
	s_addc_u32 s19, s19, s22
	s_add_u32 s18, s11, s18
	s_addc_u32 s19, s19, s21
	s_lshl_b64 s[18:19], s[18:19], 12
	v_lshl_add_u64 v[16:17], v[4:5], 0, s[18:19]
	s_add_i32 s10, s10, s17
	s_cmpk_gt_i32 s10, 0xfff
	s_waitcnt vmcnt(6)
	v_cvt_pk_bf16_f32 v6, v6, v7
	v_cvt_pk_bf16_f32 v7, v8, v9
	v_cvt_pk_bf16_f32 v8, v10, v11
	v_cvt_pk_bf16_f32 v9, v12, v13
	global_store_dwordx4 v[16:17], v[6:9], off
	s_waitcnt vmcnt(5)
	v_cvt_pk_bf16_f32 v44, v44, v45
	v_cvt_pk_bf16_f32 v45, v46, v47
	v_cvt_pk_bf16_f32 v46, v48, v49
	v_cvt_pk_bf16_f32 v47, v50, v51
	global_store_dwordx4 v[16:17], v[44:47], off offset:1024
	s_waitcnt vmcnt(4)
	v_cvt_pk_bf16_f32 v52, v52, v53
	v_cvt_pk_bf16_f32 v53, v54, v55
	v_cvt_pk_bf16_f32 v54, v56, v57
	v_cvt_pk_bf16_f32 v55, v58, v59
	global_store_dwordx4 v[16:17], v[52:55], off offset:2048
	s_waitcnt vmcnt(3)
	v_cvt_pk_bf16_f32 v60, v60, v61
	v_cvt_pk_bf16_f32 v61, v62, v63
	v_cvt_pk_bf16_f32 v62, v64, v65
	v_cvt_pk_bf16_f32 v63, v66, v67
	global_store_dwordx4 v[16:17], v[60:63], off offset:3072
	s_cbranch_scc0 .LBB0_537

; DI void kc_item(const float* src, int past, int nh, int band, int krows, bf16_t* KF, int item, int lane) {
;     const int nrb = past / 32, h = item % nh, rb = (item / nh) % nrb, b = item / (nh * nrb), r = lane & 31, hh = lane >> 5;
;     const float* sp = src + (((size_t)b * past + rb * 32 + r) * nh + h) * 64 + 8 * hh;
;     bf16_t* d = KF + (((size_t)h * (krows >> 5) + ((SEQ + b * band) >> 5) + rb) * 4 * 64 + lane) * 8;
; #pragma unroll
;     for (int ds = 0; ds < 4; ++ds) { const f32x4 v0 = *(const f32x4*)(sp + 16 * ds), v1 = *(const f32x4*)(sp + 16 * ds + 4);
;         u32x4 o; o.x = pk2(v0[0], v0[1]); o.y = pk2(v0[2], v0[3]); o.z = pk2(v1[0], v1[1]); o.w = pk2(v1[2], v1[3]);
;         *(u32x4*)(d + ds * 512) = o; }
; }
; DI void prologue_b(KArgs ap, int gw, int NGW, int lane) {
;     ...
;     for (int it = gw; it < NSTREAM * 4 * 2; it += NGW) kc_item(cbk, 128, 2, 192, KB_ROWS, (bf16_t*)(ws + WS_KB), it, lane);
.LBB0_540:
	s_lshr_b32 s7, s6, 31
	s_ashr_i32 s18, s6, 31
	s_add_i32 s7, s6, s7
	s_lshr_b32 s18, s18, 29
	s_ashr_i32 s26, s7, 1
	s_and_b32 s7, s7, -2
	s_add_i32 s19, s6, s18
	s_sub_i32 s18, s6, s7
	s_lshr_b32 s7, s26, 30
	s_add_i32 s7, s26, s7
	s_and_b32 s7, s7, -4
	s_ashr_i32 s20, s19, 3
	s_ashr_i32 s19, s18, 31
	s_sub_i32 s7, s26, s7
	s_ashr_i32 s21, s20, 31
	s_lshl_b64 s[24:25], s[18:19], 8
	s_lshl_b32 s19, s7, 5
	s_lshl_b64 s[22:23], s[20:21], 16
	s_ashr_i32 s21, s19, 31
	v_or_b32_e32 v6, s19, v0
	v_mov_b32_e32 v7, s21
	v_lshlrev_b64 v[6:7], 9, v[6:7]
	v_lshl_add_u64 v[6:7], v[2:3], 0, v[6:7]
	v_lshl_add_u64 v[6:7], v[6:7], 0, s[22:23]
	v_lshl_add_u64 v[14:15], v[6:7], 0, s[24:25]
	global_load_dwordx4 v[6:9], v[14:15], off
	global_load_dwordx4 v[10:13], v[14:15], off offset:16
	global_load_dwordx4 v[44:47], v[14:15], off offset:64
	global_load_dwordx4 v[48:51], v[14:15], off offset:80
	global_load_dwordx4 v[52:55], v[14:15], off offset:128
	global_load_dwordx4 v[56:59], v[14:15], off offset:144
	global_load_dwordx4 v[60:63], v[14:15], off offset:192
	global_load_dwordx4 v[64:67], v[14:15], off offset:208
	s_mulk_i32 s20, 0xc0
	s_addk_i32 s20, 0x4000
	s_ashr_i32 s20, s20, 5
	s_mul_hi_i32 s19, s18, 0x2c0
	s_mulk_i32 s18, 0x2c0
	s_ashr_i32 s21, s20, 31
	s_ashr_i32 s22, s7, 31
	s_add_u32 s7, s18, s7
	s_addc_u32 s19, s19, s22
	s_add_u32 s18, s7, s20
	s_addc_u32 s19, s19, s21
	s_lshl_b64 s[18:19], s[18:19], 12
	v_lshl_add_u64 v[16:17], v[4:5], 0, s[18:19]
	s_add_i32 s6, s6, s17
	s_cmpk_gt_i32 s6, 0xff
	s_waitcnt vmcnt(6)
	v_cvt_pk_bf16_f32 v6, v6, v7
	v_cvt_pk_bf16_f32 v7, v8, v9
	v_cvt_pk_bf16_f32 v8, v10, v11
	v_cvt_pk_bf16_f32 v9, v12, v13
	global_store_dwordx4 v[16:17], v[6:9], off
	s_waitcnt vmcnt(5)
	v_cvt_pk_bf16_f32 v44, v44, v45
	v_cvt_pk_bf16_f32 v45, v46, v47
	v_cvt_pk_bf16_f32 v46, v48, v49
	v_cvt_pk_bf16_f32 v47, v50, v51
	global_store_dwordx4 v[16:17], v[44:47], off offset:1024
	s_waitcnt vmcnt(4)
	v_cvt_pk_bf16_f32 v52, v52, v53
	v_cvt_pk_bf16_f32 v53, v54, v55
	v_cvt_pk_bf16_f32 v54, v56, v57
	v_cvt_pk_bf16_f32 v55, v58, v59
	global_store_dwordx4 v[16:17], v[52:55], off offset:2048
	s_waitcnt vmcnt(3)
	v_cvt_pk_bf16_f32 v60, v60, v61
	v_cvt_pk_bf16_f32 v61, v62, v63
	v_cvt_pk_bf16_f32 v62, v64, v65
	v_cvt_pk_bf16_f32 v63, v66, v67
	global_store_dwordx4 v[16:17], v[60:63], off offset:3072
	s_cbranch_scc0 .LBB0_540
